# v35 + ssm_c task head: U-stage loads issued before the Kt wait (two global round trips overlapped)
# baseline (speedup 1.0000x reference)
; #define LAS __attribute__((address_space(3)))
; template <int PMODE> __device__ __forceinline__ void ssm_c_task(unsigned char* ws, LAS unsigned char* lds, int l, int task, int tid_in) {
;     const int tid = tid_in; const int lane = tid & 63, wid = tid >> 6, rr = lane & 15, kk = lane >> 4;
;     const int g = task >> 3, cb = task & 7;
;     const bf16* U = (const bf16*)(ws + AR_U);
;     f32x4 acc[8][4];
; #pragma unroll
;     for (int a = 0; a < 8; ++a)
; #pragma unroll
;         for (int c = 0; c < 4; ++c) acc[a][c] = (f32x4){0.f, 0.f, 0.f, 0.f};
;     { const u32x4* src = (const u32x4*)((const bf16*)(ws + WS_KT) + (size_t)g * 127 * 256);
; #pragma unroll
;       for (int r = 0; r < 8; ++r) { const int c = r * 512 + tid; if (c < 127 * 32) *(LAS u32x4*)(lds + SS_KT + c * 16) = src[c]; } }
.LBB0_816:
	s_ashr_i32 s56, s54, 3
	s_mul_i32 s6, s56, 0xfe00
	v_readlane_b32 s14, v251, 34
	s_mul_hi_i32 s3, s56, 0xfe00
	v_readlane_b32 s15, v251, 35
	s_add_u32 s50, s14, s6
	s_addc_u32 s51, s15, s3
	s_mov_b64 s[100:101], exec
	s_and_b64 exec, s[100:101], vcc
	v_lshl_add_u64 v[0:1], v[136:137], 4, s[50:51]
	global_load_dwordx4 v[36:39], v[0:1], off
	s_and_b64 exec, s[100:101], s[34:35]
	v_lshl_add_u64 v[0:1], v[138:139], 4, s[50:51]
	global_load_dwordx4 v[40:43], v[0:1], off
	s_and_b64 exec, s[100:101], s[36:37]
	v_lshl_add_u64 v[0:1], v[140:141], 4, s[50:51]
	global_load_dwordx4 v[44:47], v[0:1], off
	s_and_b64 exec, s[100:101], s[38:39]
	v_lshl_add_u64 v[0:1], v[142:143], 4, s[50:51]
	global_load_dwordx4 v[48:51], v[0:1], off
	s_and_b64 exec, s[100:101], s[40:41]
	v_lshl_add_u64 v[0:1], v[144:145], 4, s[50:51]
	global_load_dwordx4 v[52:55], v[0:1], off
	s_and_b64 exec, s[100:101], s[42:43]
	v_lshl_add_u64 v[0:1], v[146:147], 4, s[50:51]
	global_load_dwordx4 v[56:59], v[0:1], off
	s_and_b64 exec, s[100:101], s[44:45]
	v_lshl_add_u64 v[0:1], v[148:149], 4, s[50:51]
	global_load_dwordx4 v[60:63], v[0:1], off
	s_and_b64 exec, s[100:101], s[46:47]
	v_lshl_add_u64 v[0:1], v[150:151], 4, s[50:51]
	global_load_dwordx4 v[64:67], v[0:1], off
	s_mov_b64 exec, s[100:101]
; #define LAS __attribute__((address_space(3)))
; __device__ __forceinline__ void ssm_stage_u(unsigned char* ws, LAS unsigned char* lds, int g, int cb, int hh, int tid) {
;     asm volatile("" : "+v"(tid));
;     const bf16* U = (const bf16*)(ws + AR_U);
;     u32x4 v[8];
; #pragma unroll
;     for (int r = 0; r < 8; ++r) { const int c = r * 512 + tid, jj = c >> 7, col = (c >> 1) & 63, part = c & 1;
;         v[r] = *(const u32x4*)(U + ((size_t)((cb * 64 + col) * 64 + hh * 32 + jj) * 512 + g * 16 + part * 8)); }
; #pragma unroll
;     for (int r = 0; r < 8; ++r) { const int c = r * 512 + tid; *(LAS u32x4*)(lds + SS_UB + c * 16) = v[r]; }
; }
; template <int PMODE> __device__ __forceinline__ void ssm_c_task(unsigned char* ws, LAS unsigned char* lds, int l, int task, int tid_in) {
;     ...
;     f32x4 acc[8][4];
; #pragma unroll
;     for (int a = 0; a < 8; ++a)
; #pragma unroll
;         for (int c = 0; c < 4; ++c) acc[a][c] = (f32x4){0.f, 0.f, 0.f, 0.f};
;     { const u32x4* src = (const u32x4*)((const bf16*)(ws + WS_KT) + (size_t)g * 127 * 256);
; #pragma unroll
;       for (int r = 0; r < 8; ++r) { const int c = r * 512 + tid; if (c < 127 * 32) *(LAS u32x4*)(lds + SS_KT + c * 16) = src[c]; } }
;     for (int hh = 0; hh < 2; ++hh) {
;         for (int rs_ = 0; rs_ < PROBE_SC_STAGE; ++rs_) { if (rs_) __syncthreads(); ssm_stage_u(ws, lds, g, cb, hh, tid); }
;         __syncthreads();
.LBB0_832:
	v_mov_b32_e32 v28, v136
	s_and_b32 s16, s54, 7
	s_lshl_b32 s88, s16, 12
	v_lshlrev_b32_e32 v0, 5, v28
	s_lshl_b32 s58, s56, 4
	v_and_b32_e32 v0, 0xfc0, v0
	s_ashr_i32 s59, s58, 31
	v_or_b32_e32 v29, s88, v0
	v_lshlrev_b32_e32 v32, 4, v28
	v_ashrrev_i32_e32 v0, 7, v28
	v_add_u32_e32 v2, 0x200, v28
	v_add_u32_e32 v8, 0x400, v28
	v_add_u32_e32 v10, 0x600, v28
	v_add_u32_e32 v16, 0x800, v28
	v_add_u32_e32 v18, 0xa00, v28
	v_add_u32_e32 v26, 0xc00, v28
	v_add_u32_e32 v28, 0xe00, v28
	s_ashr_i32 s57, s56, 31
	s_lshl_b64 s[14:15], s[58:59], 1
	v_ashrrev_i32_e32 v2, 7, v2
	v_ashrrev_i32_e32 v8, 7, v8
	v_ashrrev_i32_e32 v10, 7, v10
	v_ashrrev_i32_e32 v16, 7, v16
	v_ashrrev_i32_e32 v18, 7, v18
	v_ashrrev_i32_e32 v26, 7, v26
	v_ashrrev_i32_e32 v28, 7, v28
	s_add_u32 s60, s4, s14
	v_add_u32_e32 v0, v29, v0
	v_add_u32_e32 v2, v29, v2
	v_add_u32_e32 v8, v29, v8
	v_add_u32_e32 v10, v29, v10
	v_add_u32_e32 v16, v29, v16
	v_add_u32_e32 v18, v29, v18
	v_add_u32_e32 v26, v29, v26
	v_add_u32_e32 v28, v29, v28
	s_addc_u32 s61, s5, s15
	v_and_b32_e32 v184, 16, v32
	v_ashrrev_i32_e32 v1, 31, v0
	v_ashrrev_i32_e32 v3, 31, v2
	v_ashrrev_i32_e32 v9, 31, v8
	v_ashrrev_i32_e32 v11, 31, v10
	v_ashrrev_i32_e32 v17, 31, v16
	v_ashrrev_i32_e32 v19, 31, v18
	v_ashrrev_i32_e32 v27, 31, v26
	v_ashrrev_i32_e32 v29, 31, v28
	v_lshl_add_u64 v[24:25], s[60:61], 0, v[184:185]
	v_lshlrev_b64 v[0:1], 10, v[0:1]
	v_lshlrev_b64 v[2:3], 10, v[2:3]
	v_lshlrev_b64 v[8:9], 10, v[8:9]
	v_lshlrev_b64 v[10:11], 10, v[10:11]
	v_lshlrev_b64 v[16:17], 10, v[16:17]
	v_lshlrev_b64 v[18:19], 10, v[18:19]
	v_lshlrev_b64 v[26:27], 10, v[26:27]
	v_lshlrev_b64 v[28:29], 10, v[28:29]
	v_lshl_add_u64 v[0:1], v[24:25], 0, v[0:1]
	v_lshl_add_u64 v[4:5], v[24:25], 0, v[2:3]
	v_lshl_add_u64 v[8:9], v[24:25], 0, v[8:9]
	v_lshl_add_u64 v[12:13], v[24:25], 0, v[10:11]
	v_lshl_add_u64 v[16:17], v[24:25], 0, v[16:17]
	v_lshl_add_u64 v[20:21], v[24:25], 0, v[18:19]
	v_lshl_add_u64 v[26:27], v[24:25], 0, v[26:27]
	v_lshl_add_u64 v[28:29], v[24:25], 0, v[28:29]
	global_load_dwordx4 v[0:3], v[0:1], off
	s_nop 0
	global_load_dwordx4 v[4:7], v[4:5], off
	s_nop 0
	global_load_dwordx4 v[8:11], v[8:9], off
	s_nop 0
	global_load_dwordx4 v[12:15], v[12:13], off
	s_nop 0
	global_load_dwordx4 v[16:19], v[16:17], off
	s_nop 0
	global_load_dwordx4 v[20:23], v[20:21], off
	s_nop 0
	global_load_dwordx4 v[24:27], v[26:27], off
	s_nop 0
	global_load_dwordx4 v[28:31], v[28:29], off
	v_add_u32_e32 v32, 0, v32
	v_mov_b32_e32 v68, 0
	v_add_u32_e32 v32, 0x10000, v32
	s_mov_b32 s3, 16
	v_mov_b32_e32 v169, v220
	v_mov_b32_e32 v170, v219
	v_mov_b32_e32 v69, v68
	v_mov_b32_e32 v70, v68
	v_mov_b32_e32 v71, v68
	v_mov_b32_e32 v72, v68
	v_mov_b32_e32 v73, v68
	v_mov_b32_e32 v74, v68
	v_mov_b32_e32 v75, v68
	v_mov_b32_e32 v76, v68
	v_mov_b32_e32 v77, v68
	v_mov_b32_e32 v78, v68
	v_mov_b32_e32 v79, v68
	v_mov_b32_e32 v80, v68
	v_mov_b32_e32 v81, v68
	v_mov_b32_e32 v82, v68
	v_mov_b32_e32 v83, v68
	v_mov_b32_e32 v84, v68
	s_waitcnt vmcnt(8)
	s_and_b64 exec, s[100:101], vcc
	ds_write_b128 v223, v[36:39]
	s_and_b64 exec, s[100:101], s[34:35]
	ds_write_b128 v224, v[40:43]
	s_and_b64 exec, s[100:101], s[36:37]
	ds_write_b128 v225, v[44:47]
	s_and_b64 exec, s[100:101], s[38:39]
	ds_write_b128 v226, v[48:51]
	s_and_b64 exec, s[100:101], s[40:41]
	ds_write_b128 v227, v[52:55]
	s_and_b64 exec, s[100:101], s[42:43]
	ds_write_b128 v228, v[56:59]
	s_and_b64 exec, s[100:101], s[44:45]
	ds_write_b128 v229, v[60:63]
	s_and_b64 exec, s[100:101], s[46:47]
	ds_write_b128 v230, v[64:67]
	s_mov_b64 exec, s[100:101]
	s_waitcnt vmcnt(7)
	ds_write_b128 v32, v[0:3]
	s_waitcnt vmcnt(6)
	ds_write_b128 v32, v[4:7] offset:8192
	s_waitcnt vmcnt(5)
	ds_write_b128 v32, v[8:11] offset:16384
	s_waitcnt vmcnt(4)
	ds_write_b128 v32, v[12:15] offset:24576
	s_waitcnt vmcnt(3)
	ds_write_b128 v32, v[16:19] offset:32768
	s_waitcnt vmcnt(2)
	ds_write_b128 v32, v[20:23] offset:40960
	s_waitcnt vmcnt(1)
	ds_write_b128 v32, v[24:27] offset:49152
	s_waitcnt vmcnt(0)
	ds_write_b128 v32, v[28:31] offset:57344
	v_mov_b32_e32 v85, v68
	v_mov_b32_e32 v86, v68
	v_mov_b32_e32 v87, v68
	v_mov_b32_e32 v88, v68
	v_mov_b32_e32 v89, v68
	v_mov_b32_e32 v90, v68
	v_mov_b32_e32 v91, v68
	v_mov_b32_e32 v92, v68
	v_mov_b32_e32 v93, v68
	v_mov_b32_e32 v94, v68
	v_mov_b32_e32 v95, v68
	v_mov_b32_e32 v96, v68
	v_mov_b32_e32 v97, v68
	v_mov_b32_e32 v98, v68
	v_mov_b32_e32 v99, v68
	v_mov_b32_e32 v100, v68
	v_mov_b32_e32 v101, v68
	v_mov_b32_e32 v102, v68
	v_mov_b32_e32 v103, v68
	v_mov_b32_e32 v104, v68
	v_mov_b32_e32 v105, v68
	v_mov_b32_e32 v106, v68
	v_mov_b32_e32 v107, v68
	v_mov_b32_e32 v108, v68
	v_mov_b32_e32 v109, v68
	v_mov_b32_e32 v110, v68
	v_mov_b32_e32 v111, v68
	v_mov_b32_e32 v112, v68
	v_mov_b32_e32 v113, v68
	v_mov_b32_e32 v114, v68
	v_mov_b32_e32 v115, v68
	v_mov_b32_e32 v116, v68
	v_mov_b32_e32 v117, v68
	v_mov_b32_e32 v118, v68
	v_mov_b32_e32 v119, v68
	v_mov_b32_e32 v120, v68
	v_mov_b32_e32 v121, v68
	v_mov_b32_e32 v122, v68
	v_mov_b32_e32 v123, v68
	v_mov_b32_e32 v124, v68
	v_mov_b32_e32 v125, v68
	v_mov_b32_e32 v126, v68
	v_mov_b32_e32 v127, v68
	v_mov_b32_e32 v128, v68
	v_mov_b32_e32 v129, v68
	v_mov_b32_e32 v130, v68
	v_mov_b32_e32 v131, v68
	v_mov_b32_e32 v64, v68
	v_mov_b32_e32 v65, v68
	v_mov_b32_e32 v66, v68
	v_mov_b32_e32 v67, v68
	v_mov_b32_e32 v60, v68
	v_mov_b32_e32 v61, v68
	v_mov_b32_e32 v62, v68
	v_mov_b32_e32 v63, v68
	v_mov_b32_e32 v56, v68
	v_mov_b32_e32 v57, v68
	v_mov_b32_e32 v58, v68
	v_mov_b32_e32 v59, v68
	v_mov_b32_e32 v52, v68
	v_mov_b32_e32 v53, v68
	v_mov_b32_e32 v54, v68
	v_mov_b32_e32 v55, v68
	v_mov_b32_e32 v48, v68
	v_mov_b32_e32 v49, v68
	v_mov_b32_e32 v50, v68
	v_mov_b32_e32 v51, v68
	v_mov_b32_e32 v40, v68
	v_mov_b32_e32 v41, v68
	v_mov_b32_e32 v42, v68
	v_mov_b32_e32 v43, v68
	v_mov_b32_e32 v36, v68
	v_mov_b32_e32 v37, v68
	v_mov_b32_e32 v38, v68
	v_mov_b32_e32 v39, v68
	v_mov_b32_e32 v32, v68
	v_mov_b32_e32 v33, v68
	v_mov_b32_e32 v34, v68
	v_mov_b32_e32 v35, v68
	v_mov_b32_e32 v28, v68
	v_mov_b32_e32 v29, v68
	v_mov_b32_e32 v30, v68
	v_mov_b32_e32 v31, v68
	v_mov_b32_e32 v24, v68
	v_mov_b32_e32 v25, v68
	v_mov_b32_e32 v26, v68
	v_mov_b32_e32 v27, v68
	v_mov_b32_e32 v20, v68
	v_mov_b32_e32 v21, v68
	v_mov_b32_e32 v22, v68
	v_mov_b32_e32 v23, v68
	v_mov_b32_e32 v16, v68
	v_mov_b32_e32 v17, v68
	v_mov_b32_e32 v18, v68
	v_mov_b32_e32 v19, v68
	v_mov_b32_e32 v12, v68
	v_mov_b32_e32 v13, v68
	v_mov_b32_e32 v14, v68
	v_mov_b32_e32 v15, v68
	v_mov_b32_e32 v8, v68
	v_mov_b32_e32 v9, v68
	v_mov_b32_e32 v10, v68
	v_mov_b32_e32 v11, v68
	v_mov_b32_e32 v4, v68
	v_mov_b32_e32 v5, v68
	v_mov_b32_e32 v6, v68
	v_mov_b32_e32 v7, v68
	v_mov_b32_e32 v0, v68
	v_mov_b32_e32 v1, v68
	v_mov_b32_e32 v2, v68
	v_mov_b32_e32 v3, v68
	s_waitcnt lgkmcnt(0)
	s_barrier
